# scan rider state loads non-temporal (nt), on top of v23
# speedup vs baseline: 1.0027x; 1.0027x over previous
; __device__ __forceinline__ void attn_unit(Frame& F, const Ptrs& P, int u, int u_next, bf16x8 (&qa)[4], ScanRider& R) {
;     ...
;         const bool sc_on = R.on && R.i0 < 64;
;         u32x2 sv[8]; float sd[8];
;         unsigned svoff = (unsigned)(wid * 64 + lane) * 8u; asm volatile("" : "+v"(svoff));
;         if (sc_on) {
;             const unsigned char* SBr = (const unsigned char*)P.out; const float* DECr = (const float*)(P.ws + WS_CTL + 256 * 1024);
; #pragma unroll
;             for (int k = 0; k < 8; ++k) { const int i = R.i0 + k, c = R.dir ? 63 - i : i; const size_t bo = ((((size_t)R.b * 64 + c) * 2 + R.dir) * 16 + R.h);
;                 sv[k] = *(const u32x2*)(SBr + bo * 16384 + R.quarter * 4096 + (size_t)svoff); sd[k] = DECr[bo]; }
;         }
.LBB0_656:
	s_cmp_lt_i32 s78, 64
	s_cselect_b64 s[28:29], -1, 0
	s_cmp_gt_i32 s78, 63
	v_mov_b32_e32 v0, v185
	s_cbranch_scc1 .LBB0_658
	s_sub_i32 s83, 63, s78
	s_and_b64 s[4:5], s[8:9], exec
	s_cselect_b32 s4, s78, s83
	s_ashr_i32 s5, s4, 31
	s_lshl_b64 s[4:5], s[4:5], 5
	s_add_u32 s4, s4, s10
	s_addc_u32 s5, s5, s11
	s_lshl_b64 s[84:85], s[4:5], 14
	s_lshl_b64 s[4:5], s[4:5], 2
	v_lshl_add_u64 v[2:3], s[18:19], 0, v[0:1]
	s_add_u32 s4, s48, s4
	v_lshl_add_u64 v[4:5], v[2:3], 0, s[84:85]
	s_addc_u32 s5, s49, s5
	s_add_i32 s83, s78, 1
	s_sub_i32 s84, 62, s78
	global_load_dword v166, v1, s[4:5]
	s_and_b64 s[4:5], s[8:9], exec
	s_cselect_b32 s4, s83, s84
	s_ashr_i32 s5, s4, 31
	s_lshl_b64 s[4:5], s[4:5], 5
	s_add_u32 s4, s4, s10
	s_addc_u32 s5, s5, s11
	s_lshl_b64 s[84:85], s[4:5], 14
	s_lshl_b64 s[4:5], s[4:5], 2
	s_add_u32 s4, s48, s4
	global_load_dwordx2 v[164:165], v[4:5], off nt
	v_lshl_add_u64 v[4:5], v[2:3], 0, s[84:85]
	s_addc_u32 s5, s49, s5
	s_add_i32 s83, s78, 2
	s_sub_i32 s84, 61, s78
	global_load_dword v168, v1, s[4:5]
	s_and_b64 s[4:5], s[8:9], exec
	s_cselect_b32 s4, s83, s84
	s_ashr_i32 s5, s4, 31
	s_lshl_b64 s[4:5], s[4:5], 5
	s_add_u32 s4, s4, s10
	s_addc_u32 s5, s5, s11
	s_lshl_b64 s[84:85], s[4:5], 14
	s_lshl_b64 s[4:5], s[4:5], 2
	s_add_u32 s4, s48, s4
	global_load_dwordx2 v[170:171], v[4:5], off nt
	v_lshl_add_u64 v[4:5], v[2:3], 0, s[84:85]
	s_addc_u32 s5, s49, s5
	s_add_i32 s83, s78, 3
	s_sub_i32 s84, 60, s78
	global_load_dword v172, v1, s[4:5]
	s_and_b64 s[4:5], s[8:9], exec
	s_cselect_b32 s4, s83, s84
	s_ashr_i32 s5, s4, 31
	s_lshl_b64 s[4:5], s[4:5], 5
	s_add_u32 s4, s4, s10
	s_addc_u32 s5, s5, s11
	s_lshl_b64 s[84:85], s[4:5], 14
	s_lshl_b64 s[4:5], s[4:5], 2
	s_add_u32 s4, s48, s4
	global_load_dwordx2 v[174:175], v[4:5], off nt
	v_lshl_add_u64 v[4:5], v[2:3], 0, s[84:85]
	s_addc_u32 s5, s49, s5
	s_add_i32 s83, s78, 4
	s_sub_i32 s84, 59, s78
	global_load_dword v176, v1, s[4:5]
	s_and_b64 s[4:5], s[8:9], exec
	s_cselect_b32 s4, s83, s84
	s_ashr_i32 s5, s4, 31
	s_lshl_b64 s[4:5], s[4:5], 5
	s_add_u32 s4, s4, s10
	s_addc_u32 s5, s5, s11
	s_lshl_b64 s[84:85], s[4:5], 14
	s_lshl_b64 s[4:5], s[4:5], 2
	s_add_u32 s4, s48, s4
	global_load_dwordx2 v[178:179], v[4:5], off nt
	v_lshl_add_u64 v[4:5], v[2:3], 0, s[84:85]
	s_addc_u32 s5, s49, s5
	s_add_i32 s83, s78, 5
	s_sub_i32 s84, 58, s78
	global_load_dword v180, v1, s[4:5]
	s_and_b64 s[4:5], s[8:9], exec
	s_cselect_b32 s4, s83, s84
	s_ashr_i32 s5, s4, 31
	s_lshl_b64 s[4:5], s[4:5], 5
	s_add_u32 s4, s4, s10
	s_addc_u32 s5, s5, s11
	s_lshl_b64 s[84:85], s[4:5], 14
	s_lshl_b64 s[4:5], s[4:5], 2
	s_add_u32 s4, s48, s4
	global_load_dwordx2 v[182:183], v[4:5], off nt
	v_lshl_add_u64 v[4:5], v[2:3], 0, s[84:85]
	s_addc_u32 s5, s49, s5
	s_add_i32 s83, s78, 6
	s_sub_i32 s84, 57, s78
	global_load_dword v184, v1, s[4:5]
	s_and_b64 s[4:5], s[8:9], exec
	s_cselect_b32 s4, s83, s84
	s_ashr_i32 s5, s4, 31
	s_lshl_b64 s[4:5], s[4:5], 5
	s_add_u32 s4, s4, s10
	s_addc_u32 s5, s5, s11
	s_lshl_b64 s[84:85], s[4:5], 14
	s_lshl_b64 s[4:5], s[4:5], 2
	s_add_u32 s4, s48, s4
	global_load_dwordx2 v[186:187], v[4:5], off nt
	v_lshl_add_u64 v[4:5], v[2:3], 0, s[84:85]
	s_addc_u32 s5, s49, s5
	s_add_i32 s83, s78, 7
	s_sub_i32 s84, 56, s78
	global_load_dword v188, v1, s[4:5]
	s_and_b64 s[4:5], s[8:9], exec
	s_cselect_b32 s4, s83, s84
	s_ashr_i32 s5, s4, 31
	s_lshl_b64 s[4:5], s[4:5], 5
	s_add_u32 s4, s4, s10
	s_addc_u32 s5, s5, s11
	s_lshl_b64 s[84:85], s[4:5], 14
	s_lshl_b64 s[4:5], s[4:5], 2
	s_add_u32 s4, s48, s4
	v_lshl_add_u64 v[2:3], v[2:3], 0, s[84:85]
	s_addc_u32 s5, s49, s5
	global_load_dwordx2 v[190:191], v[4:5], off nt
	global_load_dwordx2 v[192:193], v[2:3], off nt
	global_load_dword v194, v1, s[4:5]
